# attention: no stagger, 4-slot ring, DMA three tiles ahead; long units first
# speedup vs baseline: 1.0305x; 1.0016x over previous
.Lat2_unit_1:
	s_and_b32 s4, s38, 3
	s_lshl_b32 s4, s4, 1
	s_lshr_b32 s5, s26, 1
	s_add_i32 s4, s4, s5
	s_sub_i32 s5, 15, s4
	s_bitcmp1_b32 s26, 0
	s_cselect_b32 s4, s4, s5
	s_lshl_b32 s39, s4, 2
	s_add_i32 s39, s39, 4
	s_sub_i32 s18, s39, 4
	s_lshr_b32 s5, s38, 5
	s_lshl_b32 s5, s5, 12
	s_lshl_b32 s6, s4, 8
	s_add_i32 s6, s6, s5
	s_bfe_u32 s7, s38, 0x30002
	s_lshl_b32 s14, s6, 10
	s_lshl_b32 s15, s7, 7
	s_add_i32 s14, s14, s15
	s_add_u32 s72, s54, s14
	s_addc_u32 s73, s55, 0
	s_lshl_b32 s14, s5, 10
	s_add_i32 s15, s14, s15
	s_add_i32 s15, s15, 0x2000000
	s_add_u32 s74, s54, s15
	s_addc_u32 s75, s55, 0
	s_lshr_b32 s15, s7, 1
	s_lshl_b32 s15, s15, 8
	s_add_i32 s14, s14, s15
	s_add_u32 s76, s64, s14
	s_addc_u32 s77, s65, 0
	s_lshl_b32 s14, s6, 11
	s_lshl_b32 s15, s7, 8
	s_add_i32 s14, s14, s15
	s_add_u32 s78, s50, s14
	s_addc_u32 s79, s51, 0
	global_load_dwordx4 v[148:151], v225, s[72:73] offset:0
	global_load_dwordx4 v[152:155], v225, s[72:73] offset:32
	global_load_dwordx4 v[156:159], v225, s[72:73] offset:64
	global_load_dwordx4 v[160:163], v225, s[72:73] offset:96
	s_mov_b64 s[80:81], s[74:75]
	s_mov_b64 s[82:83], s[76:77]
	s_mov_b32 s59, 0
	s_mov_b32 s60, 0x2000
	s_mov_b32 s61, 0x4000
	s_mov_b32 s25, 0x6000
	s_add_i32 s4, s59, s16
	s_mov_b32 m0, s4
	s_lshl_b32 s5, s59, 1
	global_load_lds_dwordx4 v200, s[80:81]
	s_add_i32 s5, s5, s16
	s_add_i32 s5, s5, 0x8000
	s_mov_b32 m0, s5
	s_add_i32 s5, s5, 0x2000
	global_load_lds_dwordx4 v201, s[82:83]
	s_mov_b32 m0, s5
	s_nop 0
	global_load_lds_dwordx4 v202, s[82:83]
	s_add_u32 s80, s80, 0x10000
	s_addc_u32 s81, s81, 0
	s_add_u32 s82, s82, 0x10000
	s_addc_u32 s83, s83, 0
	s_add_i32 s4, s60, s16
	s_mov_b32 m0, s4
	s_lshl_b32 s5, s60, 1
	global_load_lds_dwordx4 v200, s[80:81]
	s_add_i32 s5, s5, s16
	s_add_i32 s5, s5, 0x8000
	s_mov_b32 m0, s5
	s_add_i32 s5, s5, 0x2000
	global_load_lds_dwordx4 v201, s[82:83]
	s_mov_b32 m0, s5
	s_nop 0
	global_load_lds_dwordx4 v202, s[82:83]
	s_add_u32 s80, s80, 0x10000
	s_addc_u32 s81, s81, 0
	s_add_u32 s82, s82, 0x10000
	s_addc_u32 s83, s83, 0
	s_add_i32 s4, s61, s16
	s_mov_b32 m0, s4
	s_lshl_b32 s5, s61, 1
	global_load_lds_dwordx4 v200, s[80:81]
	s_add_i32 s5, s5, s16
	s_add_i32 s5, s5, 0x8000
	s_mov_b32 m0, s5
	s_add_i32 s5, s5, 0x2000
	global_load_lds_dwordx4 v201, s[82:83]
	s_mov_b32 m0, s5
	s_nop 0
	global_load_lds_dwordx4 v202, s[82:83]
	s_add_u32 s80, s80, 0x10000
	s_addc_u32 s81, s81, 0
	s_add_u32 s82, s82, 0x10000
	s_addc_u32 s83, s83, 0
	v_mov_b32_e32 v0, 0
	v_mov_b32_e32 v1, 0
	v_mov_b32_e32 v2, 0
	v_mov_b32_e32 v3, 0
	v_mov_b32_e32 v4, 0
	v_mov_b32_e32 v5, 0
	v_mov_b32_e32 v6, 0
	v_mov_b32_e32 v7, 0
	v_mov_b32_e32 v8, 0
	v_mov_b32_e32 v9, 0
	v_mov_b32_e32 v10, 0
	v_mov_b32_e32 v11, 0
	v_mov_b32_e32 v12, 0
	v_mov_b32_e32 v13, 0
	v_mov_b32_e32 v14, 0
	v_mov_b32_e32 v15, 0
	v_mov_b32_e32 v16, 0
	v_mov_b32_e32 v17, 0
	v_mov_b32_e32 v18, 0
	v_mov_b32_e32 v19, 0
	v_mov_b32_e32 v20, 0
	v_mov_b32_e32 v21, 0
	v_mov_b32_e32 v22, 0
	v_mov_b32_e32 v23, 0
	v_mov_b32_e32 v24, 0
	v_mov_b32_e32 v25, 0
	v_mov_b32_e32 v26, 0
	v_mov_b32_e32 v27, 0
	v_mov_b32_e32 v28, 0
	v_mov_b32_e32 v29, 0
	v_mov_b32_e32 v30, 0
	v_mov_b32_e32 v31, 0
	v_mov_b32_e32 v32, 0
	v_mov_b32_e32 v33, 0
	v_mov_b32_e32 v34, 0
	v_mov_b32_e32 v35, 0
	v_mov_b32_e32 v36, 0
	v_mov_b32_e32 v37, 0
	v_mov_b32_e32 v38, 0
	v_mov_b32_e32 v39, 0
	v_mov_b32_e32 v40, 0
	v_mov_b32_e32 v41, 0
	v_mov_b32_e32 v42, 0
	v_mov_b32_e32 v43, 0
	v_mov_b32_e32 v44, 0
	v_mov_b32_e32 v45, 0
	v_mov_b32_e32 v46, 0
	v_mov_b32_e32 v47, 0
	v_mov_b32_e32 v48, 0
	v_mov_b32_e32 v49, 0
	v_mov_b32_e32 v50, 0
	v_mov_b32_e32 v51, 0
	v_mov_b32_e32 v52, 0
	v_mov_b32_e32 v53, 0
	v_mov_b32_e32 v54, 0
	v_mov_b32_e32 v55, 0
	v_mov_b32_e32 v56, 0
	v_mov_b32_e32 v57, 0
	v_mov_b32_e32 v58, 0
	v_mov_b32_e32 v59, 0
	v_mov_b32_e32 v60, 0
	v_mov_b32_e32 v61, 0
	v_mov_b32_e32 v62, 0
	v_mov_b32_e32 v63, 0
	v_mov_b32_e32 v100, 0
	v_mov_b32_e32 v101, 0
	v_mov_b32_e32 v102, 0
	v_mov_b32_e32 v103, 0
	v_mov_b32_e32 v104, 0
	v_mov_b32_e32 v105, 0
	v_mov_b32_e32 v106, 0
	v_mov_b32_e32 v107, 0
	v_mov_b32_e32 v108, 0
	v_mov_b32_e32 v109, 0
	v_mov_b32_e32 v110, 0
	v_mov_b32_e32 v111, 0
	v_mov_b32_e32 v112, 0
	v_mov_b32_e32 v113, 0
	v_mov_b32_e32 v114, 0
	v_mov_b32_e32 v115, 0
	v_mov_b32_e32 v210, 0
	v_mov_b32_e32 v232, 0
	v_mov_b32_e32 v233, 0
	v_mov_b32_e32 v234, 0
	v_mov_b32_e32 v235, 0
	s_mov_b32 s62, 0xf149f2ca
	s_mov_b32 s47, 0xf149f2ca
	s_mov_b32 s45, 0
	s_waitcnt vmcnt(6)
	s_barrier
.Lat2_main_2:
	s_cmp_lt_u32 s45, s18
	s_cbranch_scc0 .Lat2_band_3
	v_add_u32_e32 v205, s59, v203
	ds_read_b128 v[116:119], v205 offset:0
	ds_read_b128 v[120:123], v205 offset:512
	ds_read_b128 v[124:127], v205 offset:2048
	ds_read_b128 v[128:131], v205 offset:2560
	ds_read_b128 v[132:135], v205 offset:4096
	ds_read_b128 v[136:139], v205 offset:4608
	ds_read_b128 v[140:143], v205 offset:6144
	ds_read_b128 v[144:147], v205 offset:6656
	s_add_i32 s6, s45, 3
	s_cmp_lt_u32 s6, s39
	s_cbranch_scc0 .Lat2_nodma_6
	s_add_i32 s4, s25, s16
	s_mov_b32 m0, s4
	s_lshl_b32 s5, s25, 1
	global_load_lds_dwordx4 v200, s[80:81]
	s_add_i32 s5, s5, s16
	s_add_i32 s5, s5, 0x8000
	s_mov_b32 m0, s5
	s_add_i32 s5, s5, 0x2000
	global_load_lds_dwordx4 v201, s[82:83]
	s_mov_b32 m0, s5
	s_nop 0
	global_load_lds_dwordx4 v202, s[82:83]
	s_add_u32 s80, s80, 0x10000
	s_addc_u32 s81, s81, 0
	s_add_u32 s82, s82, 0x10000
	s_addc_u32 s83, s83, 0

.Lat2_back_8:
	v_exp_f32_e32 v64, v64
	v_exp_f32_e32 v65, v65
	v_exp_f32_e32 v66, v66
	v_exp_f32_e32 v67, v67
	v_exp_f32_e32 v68, v68
	v_exp_f32_e32 v69, v69
	v_exp_f32_e32 v70, v70
	v_exp_f32_e32 v71, v71
	s_nop 0
	v_add_f32_e32 v232, v232, v64
	v_add_f32_e32 v233, v233, v65
	v_add_f32_e32 v234, v234, v66
	v_add_f32_e32 v235, v235, v67
	v_add_f32_e32 v232, v232, v68
	v_add_f32_e32 v233, v233, v69
	v_add_f32_e32 v234, v234, v70
	v_add_f32_e32 v235, v235, v71
	v_cvt_pk_bf16_f32 v64, v64, v65
	v_cvt_pk_bf16_f32 v65, v66, v67
	v_cvt_pk_bf16_f32 v66, v68, v69
	v_cvt_pk_bf16_f32 v67, v70, v71
	s_waitcnt lgkmcnt(0)
	s_nop 0
	v_mfma_f32_32x32x16_bf16 v[0:15], v[64:67], v[164:167], v[0:15]
	v_exp_f32_e32 v72, v72
	v_exp_f32_e32 v73, v73
	v_mfma_f32_32x32x16_bf16 v[16:31], v[64:67], v[168:171], v[16:31]
	ds_read_b64_tr_b16 v[164:165], v206 offset:2048
	ds_read_b64_tr_b16 v[166:167], v206 offset:2560
	v_exp_f32_e32 v74, v74
	v_exp_f32_e32 v75, v75
	v_add_f32_e32 v232, v232, v72
	v_add_f32_e32 v233, v233, v73
	v_mfma_f32_32x32x16_bf16 v[32:47], v[64:67], v[172:175], v[32:47]
	ds_read_b64_tr_b16 v[168:169], v206 offset:6144
	ds_read_b64_tr_b16 v[170:171], v206 offset:6656
	v_exp_f32_e32 v76, v76
	v_exp_f32_e32 v77, v77
	v_add_f32_e32 v234, v234, v74
	v_add_f32_e32 v235, v235, v75
	v_mfma_f32_32x32x16_bf16 v[48:63], v[64:67], v[176:179], v[48:63]
	ds_read_b64_tr_b16 v[172:173], v206 offset:10240
	ds_read_b64_tr_b16 v[174:175], v206 offset:10752
	v_exp_f32_e32 v78, v78
	v_exp_f32_e32 v79, v79
	v_add_f32_e32 v232, v232, v76
	v_add_f32_e32 v233, v233, v77
	s_nop 0
	v_add_f32_e32 v234, v234, v78
	v_add_f32_e32 v235, v235, v79
	v_cvt_pk_bf16_f32 v72, v72, v73
	v_cvt_pk_bf16_f32 v73, v74, v75
	v_cvt_pk_bf16_f32 v74, v76, v77
	v_cvt_pk_bf16_f32 v75, v78, v79
	s_nop 1
	v_mfma_f32_32x32x16_bf16 v[0:15], v[72:75], v[180:183], v[0:15]
	ds_read_b64_tr_b16 v[176:177], v206 offset:14336
	ds_read_b64_tr_b16 v[178:179], v206 offset:14848
	v_exp_f32_e32 v80, v80
	v_exp_f32_e32 v81, v81
	v_mfma_f32_32x32x16_bf16 v[16:31], v[72:75], v[184:187], v[16:31]
	ds_read_b64_tr_b16 v[180:181], v206 offset:3072
	ds_read_b64_tr_b16 v[182:183], v206 offset:3584
	v_exp_f32_e32 v82, v82
	v_exp_f32_e32 v83, v83
	v_add_f32_e32 v232, v232, v80
	v_add_f32_e32 v233, v233, v81
	v_mfma_f32_32x32x16_bf16 v[32:47], v[72:75], v[188:191], v[32:47]
	ds_read_b64_tr_b16 v[184:185], v206 offset:7168
	ds_read_b64_tr_b16 v[186:187], v206 offset:7680
	v_exp_f32_e32 v84, v84
	v_exp_f32_e32 v85, v85
	v_add_f32_e32 v234, v234, v82
	v_add_f32_e32 v235, v235, v83
	v_mfma_f32_32x32x16_bf16 v[48:63], v[72:75], v[192:195], v[48:63]
	ds_read_b64_tr_b16 v[188:189], v206 offset:11264
	ds_read_b64_tr_b16 v[190:191], v206 offset:11776
	v_exp_f32_e32 v86, v86
	v_exp_f32_e32 v87, v87
	v_add_f32_e32 v232, v232, v84
	v_add_f32_e32 v233, v233, v85
	s_nop 0
	v_add_f32_e32 v234, v234, v86
	v_add_f32_e32 v235, v235, v87
	v_cvt_pk_bf16_f32 v80, v80, v81
	v_cvt_pk_bf16_f32 v81, v82, v83
	v_cvt_pk_bf16_f32 v82, v84, v85
	v_cvt_pk_bf16_f32 v83, v86, v87
	s_nop 1
	s_waitcnt lgkmcnt(12)
	v_mfma_f32_32x32x16_bf16 v[0:15], v[80:83], v[164:167], v[0:15]
	ds_read_b64_tr_b16 v[192:193], v206 offset:15360
	ds_read_b64_tr_b16 v[194:195], v206 offset:15872
	v_exp_f32_e32 v88, v88
	v_exp_f32_e32 v89, v89
	s_waitcnt lgkmcnt(12)
	v_mfma_f32_32x32x16_bf16 v[16:31], v[80:83], v[168:171], v[16:31]
	v_exp_f32_e32 v90, v90
	v_exp_f32_e32 v91, v91
	v_add_f32_e32 v232, v232, v88
	v_add_f32_e32 v233, v233, v89
	s_waitcnt lgkmcnt(10)
	v_mfma_f32_32x32x16_bf16 v[32:47], v[80:83], v[172:175], v[32:47]
	v_exp_f32_e32 v92, v92
	v_exp_f32_e32 v93, v93
	v_add_f32_e32 v234, v234, v90
	v_add_f32_e32 v235, v235, v91
	s_waitcnt lgkmcnt(8)
	v_mfma_f32_32x32x16_bf16 v[48:63], v[80:83], v[176:179], v[48:63]
	v_exp_f32_e32 v94, v94
	v_exp_f32_e32 v95, v95
	v_add_f32_e32 v232, v232, v92
	v_add_f32_e32 v233, v233, v93
	s_nop 0
	v_add_f32_e32 v234, v234, v94
	v_add_f32_e32 v235, v235, v95
	v_cvt_pk_bf16_f32 v88, v88, v89
	v_cvt_pk_bf16_f32 v89, v90, v91
	v_cvt_pk_bf16_f32 v90, v92, v93
	v_cvt_pk_bf16_f32 v91, v94, v95
	s_nop 1
	s_waitcnt lgkmcnt(6)
	v_mfma_f32_32x32x16_bf16 v[0:15], v[88:91], v[180:183], v[0:15]
	s_waitcnt lgkmcnt(4)
	v_mfma_f32_32x32x16_bf16 v[16:31], v[88:91], v[184:187], v[16:31]
	s_waitcnt lgkmcnt(2)
	v_mfma_f32_32x32x16_bf16 v[32:47], v[88:91], v[188:191], v[32:47]
	s_waitcnt lgkmcnt(0)
	v_mfma_f32_32x32x16_bf16 v[48:63], v[88:91], v[192:195], v[48:63]
	s_add_i32 s6, s45, 3
	s_cmp_lt_u32 s6, s39
	s_cbranch_scc1 .Lat2_w6_15
	s_cmp_eq_u32 s6, s39
	s_cbranch_scc1 .Lat2_w3_13
	s_waitcnt vmcnt(0)
	s_branch .Lat2_wd_14
.Lat2_w6_15:
	s_waitcnt vmcnt(6)
	s_branch .Lat2_wd_14

.Lat2_band_3:
.Lat2_bandloop_4:
	s_sub_i32 s19, s45, s18
	v_add_u32_e32 v205, s59, v203
	ds_read_b128 v[116:119], v205 offset:0
	ds_read_b128 v[120:123], v205 offset:512
	ds_read_b128 v[124:127], v205 offset:2048
	ds_read_b128 v[128:131], v205 offset:2560
	ds_read_b128 v[132:135], v205 offset:4096
	ds_read_b128 v[136:139], v205 offset:4608
	ds_read_b128 v[140:143], v205 offset:6144
	ds_read_b128 v[144:147], v205 offset:6656
	s_add_i32 s6, s45, 3
	s_cmp_lt_u32 s6, s39
	s_cbranch_scc0 .Lat2_nodma_16
	s_add_i32 s4, s25, s16
	s_mov_b32 m0, s4
	s_lshl_b32 s5, s25, 1
	global_load_lds_dwordx4 v200, s[80:81]
	s_add_i32 s5, s5, s16
	s_add_i32 s5, s5, 0x8000
	s_mov_b32 m0, s5
	s_add_i32 s5, s5, 0x2000
	global_load_lds_dwordx4 v201, s[82:83]
	s_mov_b32 m0, s5
	s_nop 0
	global_load_lds_dwordx4 v202, s[82:83]
	s_add_u32 s80, s80, 0x10000
	s_addc_u32 s81, s81, 0
	s_add_u32 s82, s82, 0x10000
	s_addc_u32 s83, s83, 0
